# P2->P3 split seam: late-unit workgroups skip ignored generation reads, the wait behind the release atomics and the arrival-path acquire
# baseline (speedup 1.0000x reference)
; __device__ __forceinline__ unsigned xb_ld(unsigned* p)              { return __hip_atomic_load(p, __ATOMIC_RELAXED, __HIP_MEMORY_SCOPE_AGENT); }
; __device__ __forceinline__ unsigned xb_add(unsigned* p, unsigned v) { return __hip_atomic_fetch_add(p, v, __ATOMIC_RELAXED, __HIP_MEMORY_SCOPE_AGENT); }
; #define XB_SPIN(cond, bar) do { unsigned _sp = 0; while (cond) { __builtin_amdgcn_s_sleep(1); \
;     if ((++_sp & 255u) == 0u) { if (xb_ld(&(bar)[XB_TMO])) break; if (_sp > XB_SPIN_CAP) { atomicAdd(&(bar)[XB_TMO], 1u); break; } } } } while (0)
; __device__ __forceinline__ void xcd_barrier(const XcdBarrier& b) {
;     ...
;         const unsigned old = xb_add(&bar[XB_XSUB(b.x)], 1u);
;         const unsigned gen = old / nloc;
;         if (old + 1u == (gen + 1u) * nloc) {
;             __builtin_amdgcn_fence(__ATOMIC_RELEASE, "agent");
;             asm volatile("s_waitcnt vmcnt(0)" ::: "memory");
;             const unsigned og = xb_add(&bar[XB_TOP], 1u);
;             const unsigned tg = og / nx;
;             if (og + 1u == (tg + 1u) * nx) xb_add(&bar[XB_TOPGEN], 1u);
;             else XB_SPIN(xb_ld(&bar[XB_TOPGEN]) == tg, bar);
;             __builtin_amdgcn_fence(__ATOMIC_ACQUIRE, "agent");
;             xb_add(&bar[XB_XGEN(b.x)], 1u);
;             asm volatile("s_waitcnt vmcnt(0)" ::: "memory");
;         } else {
;             XB_SPIN(xb_ld(&bar[XB_XGEN(b.x)]) == gen, bar);
.LBB0_302:
	s_or_b64 exec, exec, s[38:39]
	v_cvt_f32_u32_e32 v5, v3
	s_waitcnt vmcnt(0)
	v_readfirstlane_b32 s12, v4
	v_sub_u32_e32 v4, 0, v3
	v_rcp_iflag_f32_e32 v5, v5
	v_add_u32_e32 v6, s12, v0
	v_mul_f32_e32 v5, 0x4f7ffffe, v5
	v_cvt_u32_f32_e32 v5, v5
	v_mul_lo_u32 v0, v4, v5
	v_mul_hi_u32 v0, v5, v0
	v_add_u32_e32 v0, v5, v0
	v_mul_hi_u32 v0, v6, v0
	v_mul_lo_u32 v4, v0, v3
	v_sub_u32_e32 v4, v6, v4
	v_add_u32_e32 v5, 1, v0
	v_cmp_ge_u32_e32 vcc, v4, v3
	s_nop 1
	v_cndmask_b32_e32 v0, v0, v5, vcc
	v_sub_u32_e32 v5, v4, v3
	v_cndmask_b32_e32 v4, v4, v5, vcc
	v_add_u32_e32 v5, 1, v0
	v_cmp_ge_u32_e32 vcc, v4, v3
	v_add_u32_e32 v4, 1, v6
	s_nop 0
	v_cndmask_b32_e32 v0, v0, v5, vcc
	v_mul_lo_u32 v5, v3, v0
	v_add_u32_e32 v3, v5, v3
	v_cmp_ne_u32_e32 vcc, v4, v3
	s_mov_b32 s13, -1
	s_nop 0
	v_writelane_b32 v255, s13, 47
	s_and_saveexec_b64 s[12:13], vcc
	s_xor_b64 s[38:39], exec, s[12:13]
	s_cbranch_execz .LBB0_316
	v_readlane_b32 s26, v255, 31
	s_movk_i32 s27, 0x80
	s_cmp_lt_u32 s26, s27
	s_cbranch_scc0 .Lss_fnorm
	v_readfirstlane_b32 s27, v0
	s_nop 1
	v_writelane_b32 v255, s27, 47
	s_mov_b64 vcc, 0
	s_branch .Lss_nodefer
.Lss_fnorm:
	buffer_inv sc1
	v_readlane_b32 s12, v255, 14
	v_readlane_b32 s13, v255, 15
	s_waitcnt lgkmcnt(0)
	s_nop 3
	global_load_dword v2, v1, s[12:13] sc1
	s_waitcnt vmcnt(0)
	v_cmp_eq_u32_e32 vcc, v2, v0
	v_readlane_b32 s26, v255, 31
	s_movk_i32 s27, 0x80
	s_cmp_lt_u32 s26, s27
	s_cbranch_scc0 .Lss_nodefer
	v_readfirstlane_b32 s27, v0
	s_nop 1
	v_writelane_b32 v255, s27, 47
	s_mov_b64 vcc, 0

; __device__ __forceinline__ unsigned xb_ld(unsigned* p)              { return __hip_atomic_load(p, __ATOMIC_RELAXED, __HIP_MEMORY_SCOPE_AGENT); }
; __device__ __forceinline__ unsigned xb_add(unsigned* p, unsigned v) { return __hip_atomic_fetch_add(p, v, __ATOMIC_RELAXED, __HIP_MEMORY_SCOPE_AGENT); }
; #define XB_SPIN(cond, bar) do { unsigned _sp = 0; while (cond) { __builtin_amdgcn_s_sleep(1); \
;     if ((++_sp & 255u) == 0u) { if (xb_ld(&(bar)[XB_TMO])) break; if (_sp > XB_SPIN_CAP) { atomicAdd(&(bar)[XB_TMO], 1u); break; } } } } while (0)
; __device__ __forceinline__ void xcd_barrier(const XcdBarrier& b) {
;     ...
;             const unsigned og = xb_add(&bar[XB_TOP], 1u);
;             const unsigned tg = og / nx;
;             if (og + 1u == (tg + 1u) * nx) xb_add(&bar[XB_TOPGEN], 1u);
;             else XB_SPIN(xb_ld(&bar[XB_TOPGEN]) == tg, bar);
.LBB0_319:
	s_or_b64 exec, exec, s[40:41]
	s_waitcnt vmcnt(0)
	v_readfirstlane_b32 s12, v3
	v_sub_u32_e32 v4, 0, v2
	s_mov_b64 s[40:41], -1
	v_add_u32_e32 v3, s12, v0
	v_cvt_f32_u32_e32 v0, v2
	v_readlane_b32 s12, v255, 14
	v_readlane_b32 s13, v255, 15
	v_rcp_iflag_f32_e32 v0, v0
	s_nop 0
	v_mul_f32_e32 v0, 0x4f7ffffe, v0
	v_cvt_u32_f32_e32 v0, v0
	v_mul_lo_u32 v4, v4, v0
	v_mul_hi_u32 v4, v0, v4
	v_add_u32_e32 v0, v0, v4
	v_mul_hi_u32 v0, v3, v0
	v_mul_lo_u32 v4, v0, v2
	v_sub_u32_e32 v4, v3, v4
	v_cmp_ge_u32_e32 vcc, v4, v2
	v_add_u32_e32 v5, 1, v0
	v_add_u32_e32 v3, 1, v3
	v_cndmask_b32_e32 v0, v0, v5, vcc
	v_sub_u32_e32 v5, v4, v2
	v_cndmask_b32_e32 v4, v4, v5, vcc
	v_cmp_ge_u32_e32 vcc, v4, v2
	v_add_u32_e32 v4, 1, v0
	s_nop 0
	v_cndmask_b32_e32 v0, v0, v4, vcc
	v_mul_lo_u32 v4, v2, v0
	v_add_u32_e32 v2, v4, v2
	v_cmp_ne_u32_e32 vcc, v3, v2
	v_mov_b64_e32 v[2:3], s[12:13]
	s_and_saveexec_b64 s[38:39], vcc
	s_cbranch_execz .LBB0_331
	v_readlane_b32 s12, v255, 14
	v_readlane_b32 s13, v255, 15
	s_mov_b64 s[42:43], 0
	s_nop 3
	v_readlane_b32 s26, v255, 31
	s_movk_i32 s27, 0x80
	s_cmp_lt_u32 s26, s27
	s_cbranch_scc0 .Lss_lnorm
	v_readfirstlane_b32 s27, v0
	s_nop 1
	v_writelane_b32 v255, s27, 47
	s_mov_b64 vcc, 0
	s_branch .Lss_nodefer_l
.Lss_lnorm:
	global_load_dword v2, v1, s[12:13] sc1
	s_waitcnt vmcnt(0)
	v_cmp_eq_u32_e32 vcc, v2, v0
	v_readlane_b32 s26, v255, 31
	s_movk_i32 s27, 0x80
	s_cmp_lt_u32 s26, s27
	s_cbranch_scc0 .Lss_nodefer_l
	v_readfirstlane_b32 s27, v0
	s_nop 1
	v_writelane_b32 v255, s27, 47
	s_mov_b64 vcc, 0

; __device__ __forceinline__ unsigned xb_ld(unsigned* p)              { return __hip_atomic_load(p, __ATOMIC_RELAXED, __HIP_MEMORY_SCOPE_AGENT); }
; __device__ __forceinline__ unsigned xb_add(unsigned* p, unsigned v) { return __hip_atomic_fetch_add(p, v, __ATOMIC_RELAXED, __HIP_MEMORY_SCOPE_AGENT); }
; #define XB_SPIN(cond, bar) do { unsigned _sp = 0; while (cond) { __builtin_amdgcn_s_sleep(1); \
;     if ((++_sp & 255u) == 0u) { if (xb_ld(&(bar)[XB_TMO])) break; if (_sp > XB_SPIN_CAP) { atomicAdd(&(bar)[XB_TMO], 1u); break; } } } } while (0)
; __device__ __forceinline__ void xcd_barrier(const XcdBarrier& b) {
;     ...
;             __builtin_amdgcn_fence(__ATOMIC_ACQUIRE, "agent");
;             xb_add(&bar[XB_XGEN(b.x)], 1u);
;             asm volatile("s_waitcnt vmcnt(0)" ::: "memory");
;         } else {
;             XB_SPIN(xb_ld(&bar[XB_XGEN(b.x)]) == gen, bar);
;             __builtin_amdgcn_fence(__ATOMIC_ACQUIRE, "agent");
;             asm volatile("s_waitcnt vmcnt(0)" ::: "memory");
;         }
;     }
;     __syncthreads();
.LBB0_333:
	s_or_b64 exec, exec, s[38:39]
	s_mov_b64 s[38:39], exec
	v_mbcnt_lo_u32_b32 v0, s38, 0
	v_mbcnt_hi_u32_b32 v0, s39, v0
	v_cmp_eq_u32_e32 vcc, 0, v0
	v_readlane_b32 s26, v255, 31
	s_movk_i32 s27, 0x80
	s_cmp_lt_u32 s26, s27
	s_cbranch_scc1 .Lss_lskip1
	s_waitcnt vmcnt(0)
.Lss_lskip1:
	s_and_saveexec_b64 s[40:41], vcc
	s_cbranch_execz .LBB0_335
	s_bcnt1_i32_b64 s12, s[38:39]
	v_mov_b32_e32 v0, s12
	v_readlane_b32 s12, v255, 10
	v_readlane_b32 s13, v255, 11
	s_nop 4
	global_atomic_add v1, v0, s[12:13]
.LBB0_335:
	s_or_b64 exec, exec, s[40:41]
	v_readlane_b32 s26, v255, 31
	s_movk_i32 s27, 0x80
	s_cmp_lt_u32 s26, s27
	s_cbranch_scc1 .Lss_lskip2
	buffer_inv sc1
	s_waitcnt vmcnt(0)
.Lss_lskip2:
.LBB0_336:
	s_or_b64 exec, exec, s[36:37]
	s_waitcnt lgkmcnt(0)
	s_barrier
